# mLSTM scan diagonal S^T chains: q|k fragments read straight into MFMA operand order with two register sets (no v_mov shuffles, next step in flight); DPP prefix scans; adaLN load batching; attention co
# speedup vs baseline: 1.0055x; 1.0034x over previous
; #define LAS __attribute__((address_space(3)))
; #define MFMA32(a, b, c) __builtin_amdgcn_mfma_f32_32x32x16_bf16((a), (b), (c), 0, 0, 0)
; #define DOT2(a, b, c) dot2_bf16((a), (b), (c))
; DI bf16x8 pack_step(const f32x16& x, int s) { u32x4 p = {pk2(x[8 * s], x[8 * s + 1]), pk2(x[8 * s + 2], x[8 * s + 3]), pk2(x[8 * s + 4], x[8 * s + 5]), pk2(x[8 * s + 6], x[8 * s + 7])}; return __builtin_bit_cast(bf16x8, p); }
; DI bf16x8 ldsfrag(const LAS unsigned char* buf, unsigned o) { const s16x4 lo = *(const LAS s16x4*)(buf + o), hi = *(const LAS s16x4*)(buf + (o ^ 16u)); return __builtin_shufflevector(lo, hi, 0, 1, 2, 3, 4, 5, 6, 7); }
; DI void scan_phase(const Args& A, LAS unsigned char* lds, int wv) {
;     ...
;             const int sbase = dir ? 63 - h4 : h4, sgn = dir ? -1 : 1;
; #pragma unroll
;             for (int tb = 0; tb < 2; ++tb) {
;                 __builtin_amdgcn_sched_barrier(0);
;                 const unsigned qo = qro + tb * 8192u;
;                 f32x16 ha;
; #pragma unroll
;                 for (int i = 0; i < 16; ++i) ha[i] = 0.f;
;                 float qnv = 0.f;
; #pragma unroll
;                 for (int kk = 0; kk < 8; ++kk) {
;                     const bf16x8 qa = ldsfrag(Qb, qo + (((2u * kk) ^ xr) << 4));
;                     ha = MFMA32(qa, pack_step(cacc[kk >> 1], kk & 1), ha);
;                     { const u32x2 nb0 = *(const LAS u32x2*)(nbh + 8 * kk), nb1 = *(const LAS u32x2*)(nbh + 8 * kk + 4); const u32x4 qw = __builtin_bit_cast(u32x4, qa);
;                       qnv = DOT2(qw.x, nb0.x, qnv); qnv = DOT2(qw.y, nb0.y, qnv); qnv = DOT2(qw.z, nb1.x, qnv); qnv = DOT2(qw.w, nb1.y, qnv); }
;                 }
.LBB0_1229:
	s_or_b64 exec, exec, s[6:7]
	v_xor_b32_e32 v65, 63, v192
	v_cndmask_b32_e64 v175, v65, v192, s[4:5]
	v_xor_b32_e32 v65, 32, v151
	s_bitcmp1_b32 s80, 0
	s_waitcnt lgkmcnt(0)
	v_cmp_lt_i32_e32 vcc, v65, v64
	s_cselect_b32 s6, 0xc000, 0
	v_lshlrev_b32_e32 v92, 4, v172
	v_cndmask_b32_e32 v64, v151, v65, vcc
	v_lshl_add_u32 v174, v192, 2, s47
	v_lshl_or_b32 v193, v164, 8, v144
	v_lshl_add_u32 v168, v164, 2, s47
	s_add_i32 s10, s6, 0
	v_and_b32_e32 v194, 0xf0, v92
	v_lshlrev_b32_e32 v169, 2, v64
	v_add_u32_e32 v84, s47, v144
	v_or_b32_e32 v64, v193, v194
	v_add_u32_e32 v176, s10, v64
	v_bitop3_b32 v64, v193, 16, v194 bitop3:0x36
	v_add_u32_e32 v177, s10, v64
	ds_read_b64 v[80:81], v176
	ds_read_b64 v[82:83], v177
	v_add_u32_e32 v170, 0x800, v84
	ds_read2_b64 v[84:87], v170 offset1:2
	ds_read2_b64 v[88:91], v170 offset0:4 offset1:6
	v_mov_b32_e32 v147, v145
	s_waitcnt lgkmcnt(0)
	v_dot2c_f32_bf16 v147, v80, v84
	v_cvt_pk_bf16_f32 v112, v0, v1
	v_cvt_pk_bf16_f32 v113, v2, v3
	v_cvt_pk_bf16_f32 v114, v4, v5
	v_cvt_pk_bf16_f32 v115, v6, v7
	v_dot2c_f32_bf16 v147, v81, v85
	v_bitop3_b32 v195, v92, 32, v157 bitop3:0x6c
	v_dot2c_f32_bf16 v147, v82, v86
	v_cvt_pk_bf16_f32 v116, v8, v9
	v_mfma_f32_32x32x16_bf16 v[64:79], v[80:83], v[112:115], 0
	v_or_b32_e32 v80, v193, v195
	v_bitop3_b32 v82, v193, 16, v195 bitop3:0x36
	v_add_u32_e32 v190, s10, v80
	v_add_u32_e32 v191, s10, v82
	v_dot2c_f32_bf16 v147, v83, v87
	ds_read_b64 v[80:81], v190
	ds_read_b64 v[82:83], v191
	s_waitcnt lgkmcnt(0)
	v_dot2c_f32_bf16 v147, v80, v88
	v_cvt_pk_bf16_f32 v117, v10, v11
	v_cvt_pk_bf16_f32 v118, v12, v13
	v_cvt_pk_bf16_f32 v119, v14, v15
	v_dot2c_f32_bf16 v147, v81, v89
	v_bitop3_b32 v196, v92, 64, v157 bitop3:0x6c
	v_dot2c_f32_bf16 v147, v82, v90
	ds_read2_b64 v[84:87], v170 offset0:8 offset1:10
	v_mfma_f32_32x32x16_bf16 v[64:79], v[80:83], v[116:119], v[64:79]
	v_or_b32_e32 v80, v193, v196
	v_bitop3_b32 v82, v193, 16, v196 bitop3:0x36
	v_add_u32_e32 v188, s10, v80
	v_add_u32_e32 v189, s10, v82
	v_dot2c_f32_bf16 v147, v83, v91
	ds_read_b64 v[80:81], v188
	ds_read_b64 v[82:83], v189
	s_waitcnt lgkmcnt(0)
	v_dot2c_f32_bf16 v147, v80, v84
	v_cvt_pk_bf16_f32 v120, v16, v17
	v_cvt_pk_bf16_f32 v121, v18, v19
	v_cvt_pk_bf16_f32 v122, v20, v21
	v_cvt_pk_bf16_f32 v123, v22, v23
	v_dot2c_f32_bf16 v147, v81, v85
	v_bitop3_b32 v197, v92, s16, v157 bitop3:0x6c
	v_dot2c_f32_bf16 v147, v82, v86
	s_movk_i32 s6, 0x80
	v_mfma_f32_32x32x16_bf16 v[64:79], v[80:83], v[120:123], v[64:79]
	v_or_b32_e32 v80, v193, v197
	v_bitop3_b32 v82, v193, 16, v197 bitop3:0x36
	v_add_u32_e32 v186, s10, v80
	v_add_u32_e32 v187, s10, v82
	v_dot2c_f32_bf16 v147, v83, v87
	ds_read_b64 v[80:81], v186
	ds_read_b64 v[82:83], v187
	ds_read2_b64 v[84:87], v170 offset0:12 offset1:14
	s_waitcnt lgkmcnt(0)
	v_dot2c_f32_bf16 v147, v80, v84
	v_cvt_pk_bf16_f32 v124, v24, v25
	v_cvt_pk_bf16_f32 v125, v26, v27
	v_cvt_pk_bf16_f32 v126, v28, v29
	v_cvt_pk_bf16_f32 v127, v30, v31
	v_dot2c_f32_bf16 v147, v81, v85
	v_bitop3_b32 v198, v92, s6, v157 bitop3:0x6c
	v_dot2c_f32_bf16 v147, v82, v86
	s_movk_i32 s6, 0xa0
	v_mfma_f32_32x32x16_bf16 v[64:79], v[80:83], v[124:127], v[64:79]
	v_or_b32_e32 v80, v193, v198
	v_bitop3_b32 v82, v193, 16, v198 bitop3:0x36
	v_add_u32_e32 v184, s10, v80
	v_add_u32_e32 v185, s10, v82
	v_dot2c_f32_bf16 v147, v83, v87
	ds_read_b64 v[80:81], v184
	ds_read_b64 v[82:83], v185
	ds_read2_b64 v[84:87], v170 offset0:16 offset1:18
	s_waitcnt lgkmcnt(0)
	v_dot2c_f32_bf16 v147, v80, v84
	v_cvt_pk_bf16_f32 v128, v32, v33
	v_cvt_pk_bf16_f32 v129, v34, v35
	v_cvt_pk_bf16_f32 v130, v36, v37
	v_cvt_pk_bf16_f32 v131, v38, v39
	v_dot2c_f32_bf16 v147, v81, v85
	v_bitop3_b32 v199, v92, s6, v157 bitop3:0x6c
	v_dot2c_f32_bf16 v147, v82, v86
	s_movk_i32 s6, 0xc0
	v_mfma_f32_32x32x16_bf16 v[64:79], v[80:83], v[128:131], v[64:79]
	v_or_b32_e32 v80, v193, v199
	v_bitop3_b32 v82, v193, 16, v199 bitop3:0x36
	v_add_u32_e32 v182, s10, v80
	v_add_u32_e32 v183, s10, v82
	v_dot2c_f32_bf16 v147, v83, v87
	ds_read_b64 v[80:81], v182
	ds_read_b64 v[82:83], v183
	ds_read2_b64 v[84:87], v170 offset0:20 offset1:22
	s_waitcnt lgkmcnt(0)
	v_dot2c_f32_bf16 v147, v80, v84
	v_cvt_pk_bf16_f32 v132, v40, v41
	v_cvt_pk_bf16_f32 v133, v42, v43
	v_cvt_pk_bf16_f32 v134, v44, v45
	v_cvt_pk_bf16_f32 v135, v46, v47
	v_dot2c_f32_bf16 v147, v81, v85
	v_bitop3_b32 v200, v92, s6, v157 bitop3:0x6c
	v_dot2c_f32_bf16 v147, v82, v86
	s_movk_i32 s6, 0xe0
	v_mfma_f32_32x32x16_bf16 v[64:79], v[80:83], v[132:135], v[64:79]
	v_or_b32_e32 v80, v193, v200
	v_bitop3_b32 v82, v193, 16, v200 bitop3:0x36
	v_add_u32_e32 v180, s10, v80
	v_add_u32_e32 v181, s10, v82
	v_dot2c_f32_bf16 v147, v83, v87
	ds_read_b64 v[80:81], v180
	ds_read_b64 v[82:83], v181
	ds_read2_b64 v[84:87], v170 offset0:24 offset1:26
	s_waitcnt lgkmcnt(0)
	v_dot2c_f32_bf16 v147, v80, v84
	v_cvt_pk_bf16_f32 v136, v48, v49
	v_cvt_pk_bf16_f32 v137, v50, v51
	v_cvt_pk_bf16_f32 v138, v52, v53
	v_cvt_pk_bf16_f32 v139, v54, v55
	v_dot2c_f32_bf16 v147, v81, v85
	v_bitop3_b32 v201, v92, s6, v157 bitop3:0x6c
	v_dot2c_f32_bf16 v147, v82, v86
	v_cvt_pk_bf16_f32 v140, v56, v57
	v_mfma_f32_32x32x16_bf16 v[64:79], v[80:83], v[136:139], v[64:79]
	v_or_b32_e32 v80, v193, v201
	v_bitop3_b32 v82, v193, 16, v201 bitop3:0x36
	v_add_u32_e32 v178, s10, v80
	v_add_u32_e32 v179, s10, v82
	v_dot2c_f32_bf16 v147, v83, v87
	ds_read_b64 v[80:81], v178
	ds_read_b64 v[82:83], v179
	v_cvt_pk_bf16_f32 v141, v58, v59
	v_cvt_pk_bf16_f32 v142, v60, v61
	v_cvt_pk_bf16_f32 v143, v62, v63
	ds_read2_b64 v[84:87], v170 offset0:28 offset1:30
	s_waitcnt lgkmcnt(0)
; #define LAS __attribute__((address_space(3)))
; #define MFMA32(a, b, c) __builtin_amdgcn_mfma_f32_32x32x16_bf16((a), (b), (c), 0, 0, 0)
; DI bf16x8 pack_step(const f32x16& x, int s) { u32x4 p = {pk2(x[8 * s], x[8 * s + 1]), pk2(x[8 * s + 2], x[8 * s + 3]), pk2(x[8 * s + 4], x[8 * s + 5]), pk2(x[8 * s + 6], x[8 * s + 7])}; return __builtin_bit_cast(bf16x8, p); }
; DI bf16x8 ldsfrag(const LAS unsigned char* buf, unsigned o) { const s16x4 lo = *(const LAS s16x4*)(buf + o), hi = *(const LAS s16x4*)(buf + (o ^ 16u)); return __builtin_shufflevector(lo, hi, 0, 1, 2, 3, 4, 5, 6, 7); }
; DI void scan_phase(const Args& A, LAS unsigned char* lds, int wv) {
;     ...
;                 qnv += __shfl_xor(qnv, 32);
; #pragma unroll
;                 for (int g = 0; g < 4; ++g) { const f32x4 av = *(const LAS f32x4*)(wh + 128 + 32 * tb + 8 * g);
; #pragma unroll
;                     for (int q = 0; q < 4; ++q) ha[4 * g + q] *= av[q]; }
;                 const float pmt = wr[64 + 32 * tb];
;                 const int tp = dir ? (63 - 32 * tb) - rj : 32 * tb + rj;
;                 float ds = 0.f;
; #pragma unroll
;                 for (int sb = 0; sb < 2; ++sb) {
;                     __builtin_amdgcn_sched_barrier(0);
;                     if (sb != tb && (dir ? sb < tb : sb > tb)) continue;
;                     const unsigned ko = qro + sb * 8192u;
;                     f32x16 st;
; #pragma unroll
;                     for (int i = 0; i < 16; ++i) st[i] = 0.f;
; #pragma unroll
;                     for (int kk = 0; kk < 8; ++kk) { const unsigned c = ((2u * kk) ^ xr) << 4; st = MFMA32(ldsfrag(Kb, ko + c), ldsfrag(Qb, qo + c), st); }
; #pragma unroll
;                     for (int g = 0; g < 4; ++g) { const f32x4 uv = *(const LAS f32x4*)(wh + 32 * sb + 8 * g);
; #pragma unroll
;                         for (int q = 0; q < 4; ++q) {
;                             const int sc = 32 * sb + q + 8 * g;
;                             const int sp = sbase + sgn * sc;
;                             st[4 * g + q] *= __builtin_amdgcn_exp2f((sp <= tp) ? uv[q] - pmt : -1e30f);
;                             ds += st[4 * g + q];
;                         } }
;                     ha = MFMA32(pack_step(st, 0), vf[2 * sb], ha);
;                     ha = MFMA32(pack_step(st, 1), vf[2 * sb + 1], ha);
	v_dot2c_f32_bf16 v147, v80, v84
	v_mfma_f32_32x32x16_bf16 v[64:79], v[80:83], v[140:143], v[64:79]
	v_dot2c_f32_bf16 v147, v81, v85
	s_nop 0
	v_dot2c_f32_bf16 v147, v82, v86
	s_nop 0
	v_dot2c_f32_bf16 v147, v83, v87
	ds_read_b128 v[80:83], v174 offset:512
	ds_read_b128 v[84:87], v174 offset:544
	ds_read_b128 v[88:91], v174 offset:576
	ds_read_b128 v[92:95], v174 offset:608
	ds_bpermute_b32 v149, v169, v147
	ds_read_b32 v148, v168 offset:256
	s_waitcnt lgkmcnt(0)
	s_nop 2
	v_pk_mul_f32 v[64:65], v[64:65], v[80:81]
	v_xor_b32_e32 v80, 63, v164
	v_cndmask_b32_e64 v80, v80, v164, s[4:5]
	v_pk_mul_f32 v[78:79], v[78:79], v[94:95]
	v_pk_mul_f32 v[76:77], v[76:77], v[92:93]
	v_pk_mul_f32 v[74:75], v[74:75], v[90:91]
	v_pk_mul_f32 v[72:73], v[72:73], v[88:89]
	v_pk_mul_f32 v[70:71], v[70:71], v[86:87]
	v_pk_mul_f32 v[68:69], v[68:69], v[84:85]
	v_pk_mul_f32 v[66:67], v[66:67], v[82:83]
	v_sub_u32_e32 v202, v80, v175
	ds_read_b64 v[204:205], v176
	ds_read_b64 v[206:207], v177
	ds_read_b64 v[212:213], v176 offset:16384
	ds_read_b64 v[214:215], v177 offset:16384
	ds_read_b64 v[252:253], v190
	ds_read_b64 v[254:255], v191
	ds_read_b64 v[248:249], v190 offset:16384
	ds_read_b64 v[250:251], v191 offset:16384
	v_cmp_lt_i32_e32 vcc, -1, v202
	s_waitcnt lgkmcnt(4)
	v_mfma_f32_32x32x16_bf16 v[80:95], v[212:215], v[204:207], 0
	ds_read_b64 v[204:205], v188
	ds_read_b64 v[206:207], v189
	ds_read_b64 v[212:213], v188 offset:16384
	ds_read_b64 v[214:215], v189 offset:16384
	s_waitcnt lgkmcnt(4)
	v_mfma_f32_32x32x16_bf16 v[80:95], v[248:251], v[252:255], v[80:95]
	ds_read_b64 v[252:253], v186
	ds_read_b64 v[254:255], v187
	ds_read_b64 v[248:249], v186 offset:16384
	ds_read_b64 v[250:251], v187 offset:16384
	s_waitcnt lgkmcnt(4)
	v_mfma_f32_32x32x16_bf16 v[80:95], v[212:215], v[204:207], v[80:95]
	ds_read_b64 v[204:205], v184
	ds_read_b64 v[206:207], v185
	ds_read_b64 v[212:213], v184 offset:16384
	ds_read_b64 v[214:215], v185 offset:16384
	s_waitcnt lgkmcnt(4)
	v_mfma_f32_32x32x16_bf16 v[80:95], v[248:251], v[252:255], v[80:95]
	ds_read_b64 v[252:253], v182
	ds_read_b64 v[254:255], v183
	ds_read_b64 v[248:249], v182 offset:16384
	ds_read_b64 v[250:251], v183 offset:16384
	s_waitcnt lgkmcnt(4)
	v_mfma_f32_32x32x16_bf16 v[80:95], v[212:215], v[204:207], v[80:95]
	ds_read_b64 v[204:205], v180
	ds_read_b64 v[206:207], v181
	ds_read_b64 v[212:213], v180 offset:16384
	ds_read_b64 v[214:215], v181 offset:16384
	s_waitcnt lgkmcnt(4)
	v_mfma_f32_32x32x16_bf16 v[80:95], v[248:251], v[252:255], v[80:95]
	ds_read_b64 v[252:253], v178
	ds_read_b64 v[254:255], v179
	ds_read_b64 v[248:249], v178 offset:16384
	ds_read_b64 v[250:251], v179 offset:16384
	s_waitcnt lgkmcnt(4)
	v_mfma_f32_32x32x16_bf16 v[80:95], v[212:215], v[204:207], v[80:95]
	s_waitcnt lgkmcnt(0)
	v_mfma_f32_32x32x16_bf16 v[80:95], v[248:251], v[252:255], v[80:95]
	ds_read_b128 v[204:207], v174
	ds_read_b128 v[208:211], v174 offset:32
	s_waitcnt lgkmcnt(0)
	v_sub_f32_e32 v146, v204, v148
	v_cndmask_b32_e32 v146, v158, v146, vcc
	v_exp_f32_e32 v204, v146
	v_sub_f32_e32 v146, v205, v148
	v_cmp_le_i32_e32 vcc, s46, v202
	v_sub_f32_e32 v203, v206, v148
	s_nop 0
	v_cndmask_b32_e32 v146, v158, v146, vcc
	v_exp_f32_e32 v205, v146
	v_cmp_le_i32_e32 vcc, s0, v202
	v_pk_mul_f32 v[80:81], v[80:81], v[204:205]
	s_nop 0
	v_cndmask_b32_e32 v203, v158, v203, vcc
	v_exp_f32_e32 v204, v203
	v_sub_f32_e32 v203, v207, v148
	v_cmp_le_i32_e32 vcc, s1, v202
	v_add_f32_e32 v146, 0, v80
	v_add_f32_e32 v146, v81, v146
	v_cndmask_b32_e32 v203, v158, v203, vcc
	v_exp_f32_e32 v205, v203
	v_sub_f32_e32 v203, v208, v148
	v_cmp_le_i32_e32 vcc, s93, v202
	v_cvt_pk_bf16_f32 v80, v80, v81
	v_pk_mul_f32 v[82:83], v[82:83], v[204:205]
	v_cndmask_b32_e32 v203, v158, v203, vcc
	v_exp_f32_e32 v204, v203
	v_sub_f32_e32 v203, v209, v148
	v_cmp_le_i32_e32 vcc, s54, v202
	v_add_f32_e32 v146, v82, v146
	v_add_f32_e32 v146, v83, v146
	v_cndmask_b32_e32 v203, v158, v203, vcc
	v_exp_f32_e32 v205, v203
	v_sub_f32_e32 v203, v210, v148
	v_cmp_le_i32_e32 vcc, s30, v202
	v_cvt_pk_bf16_f32 v81, v82, v83
	v_pk_mul_f32 v[84:85], v[84:85], v[204:205]
	v_cndmask_b32_e32 v203, v158, v203, vcc
	v_exp_f32_e32 v204, v203
	v_sub_f32_e32 v203, v211, v148
	v_cmp_le_i32_e32 vcc, s31, v202
	v_add_f32_e32 v146, v84, v146
	v_add_f32_e32 v146, v85, v146
	v_cndmask_b32_e32 v203, v158, v203, vcc
	v_exp_f32_e32 v205, v203
	v_cmp_le_i32_e32 vcc, s55, v202
	v_cvt_pk_bf16_f32 v82, v84, v85
	v_pk_mul_f32 v[86:87], v[86:87], v[204:205]
	ds_read_b128 v[204:207], v174 offset:64
	v_add_f32_e32 v146, v86, v146
	v_add_f32_e32 v146, v87, v146
	v_cvt_pk_bf16_f32 v83, v86, v87
	s_waitcnt lgkmcnt(0)
	v_sub_f32_e32 v203, v204, v148
	v_cndmask_b32_e32 v203, v158, v203, vcc
	v_exp_f32_e32 v204, v203
	v_sub_f32_e32 v203, v205, v148
	v_cmp_le_i32_e32 vcc, s34, v202
	s_waitcnt vmcnt(0)
	v_mfma_f32_32x32x16_bf16 v[64:79], v[80:83], v[108:111], v[64:79]
	v_cndmask_b32_e32 v203, v158, v203, vcc
	v_exp_f32_e32 v205, v203
	v_cmp_le_i32_e32 vcc, s97, v202
	v_pk_mul_f32 v[204:205], v[88:89], v[204:205]
	s_nop 0
	v_add_f32_e32 v88, v204, v146
	v_add_f32_e32 v146, v205, v88
	v_sub_f32_e32 v88, v206, v148
	v_cndmask_b32_e32 v88, v158, v88, vcc
	v_sub_f32_e32 v89, v207, v148
	v_cmp_le_i32_e32 vcc, s52, v202
	v_exp_f32_e32 v88, v88
	v_cvt_pk_bf16_f32 v80, v204, v205
	v_cndmask_b32_e32 v89, v158, v89, vcc
	v_exp_f32_e32 v89, v89
	v_cmp_le_i32_e32 vcc, s60, v202
	v_pk_mul_f32 v[206:207], v[90:91], v[88:89]
	s_nop 0
	v_add_f32_e32 v88, v206, v146
	v_add_f32_e32 v146, v207, v88
	ds_read_b128 v[88:91], v174 offset:96
	v_cvt_pk_bf16_f32 v81, v206, v207
	s_waitcnt lgkmcnt(0)
	v_sub_f32_e32 v88, v88, v148
	v_cndmask_b32_e32 v88, v158, v88, vcc
	v_sub_f32_e32 v89, v89, v148
	v_cmp_le_i32_e32 vcc, s35, v202
	v_sub_f32_e32 v90, v90, v148
	v_sub_f32_e32 v91, v91, v148
	v_cndmask_b32_e32 v89, v158, v89, vcc
	v_cmp_le_i32_e32 vcc, s56, v202
	v_exp_f32_e32 v88, v88
	v_exp_f32_e32 v89, v89
	v_cndmask_b32_e32 v90, v158, v90, vcc
	v_cmp_le_i32_e32 vcc, s92, v202
	v_exp_f32_e32 v90, v90
	v_pk_mul_f32 v[88:89], v[92:93], v[88:89]
	v_cndmask_b32_e32 v91, v158, v91, vcc
	v_exp_f32_e32 v91, v91
	v_cvt_pk_bf16_f32 v82, v88, v89
	v_add_f32_e32 v92, v88, v146
	v_add_f32_e32 v92, v89, v92
	v_pk_mul_f32 v[90:91], v[94:95], v[90:91]
	s_nop 0
	v_cvt_pk_bf16_f32 v83, v90, v91
	v_add_f32_e32 v92, v90, v92
	v_add_f32_e32 v146, v91, v92
	v_mfma_f32_32x32x16_bf16 v[64:79], v[80:83], v[104:107], v[64:79]
	s_andn2_b64 vcc, exec, s[22:23]
	v_or_b32_e32 v203, 0x2000, v193
	s_cbranch_vccnz .LBB0_1231
; #define LAS __attribute__((address_space(3)))
; #define MFMA32(a, b, c) __builtin_amdgcn_mfma_f32_32x32x16_bf16((a), (b), (c), 0, 0, 0)
; DI bf16x8 pack_step(const f32x16& x, int s) { u32x4 p = {pk2(x[8 * s], x[8 * s + 1]), pk2(x[8 * s + 2], x[8 * s + 3]), pk2(x[8 * s + 4], x[8 * s + 5]), pk2(x[8 * s + 6], x[8 * s + 7])}; return __builtin_bit_cast(bf16x8, p); }
; DI bf16x8 ldsfrag(const LAS unsigned char* buf, unsigned o) { const s16x4 lo = *(const LAS s16x4*)(buf + o), hi = *(const LAS s16x4*)(buf + (o ^ 16u)); return __builtin_shufflevector(lo, hi, 0, 1, 2, 3, 4, 5, 6, 7); }
; DI void scan_phase(const Args& A, LAS unsigned char* lds, int wv) {
;     ...
;                 for (int sb = 0; sb < 2; ++sb) {
;                     __builtin_amdgcn_sched_barrier(0);
;                     if (sb != tb && (dir ? sb < tb : sb > tb)) continue;
;                     const unsigned ko = qro + sb * 8192u;
;                     f32x16 st;
; #pragma unroll
;                     for (int i = 0; i < 16; ++i) st[i] = 0.f;
; #pragma unroll
;                     for (int kk = 0; kk < 8; ++kk) { const unsigned c = ((2u * kk) ^ xr) << 4; st = MFMA32(ldsfrag(Kb, ko + c), ldsfrag(Qb, qo + c), st); }
; #pragma unroll
;                     for (int g = 0; g < 4; ++g) { const f32x4 uv = *(const LAS f32x4*)(wh + 32 * sb + 8 * g);
; #pragma unroll
;                         for (int q = 0; q < 4; ++q) {
;                             const int sc = 32 * sb + q + 8 * g;
;                             const int sp = sbase + sgn * sc;
;                             st[4 * g + q] *= __builtin_amdgcn_exp2f((sp <= tp) ? uv[q] - pmt : -1e30f);
;                             ds += st[4 * g + q];
;                         } }
;                     ha = MFMA32(pack_step(st, 0), vf[2 * sb], ha);
;                     ha = MFMA32(pack_step(st, 1), vf[2 * sb + 1], ha);
	v_add3_u32 v80, v193, v194, s10
	ds_read_b64 v[80:81], v80 offset:24576
	v_or_b32_e32 v82, v203, v194
	v_xad_u32 v82, v82, 16, s10
	ds_read_b64 v[82:83], v82 offset:16384
	ds_read_b64 v[84:85], v176
	ds_read_b64 v[86:87], v177
	v_add3_u32 v204, v193, v195, s10
	ds_read_b64 v[204:205], v204 offset:24576
	v_or_b32_e32 v206, v203, v195
	v_xad_u32 v206, v206, 16, s10
	ds_read_b64 v[206:207], v206 offset:16384
	ds_read_b64 v[208:209], v190
	ds_read_b64 v[210:211], v191
	s_waitcnt lgkmcnt(4)
	v_mfma_f32_32x32x16_bf16 v[80:95], v[80:83], v[84:87], 0
	s_movk_i32 s6, 0xffdf
	v_cmp_lt_i32_e32 vcc, s6, v202
	s_movk_i32 s6, 0xffde
	s_waitcnt lgkmcnt(0)
	v_mfma_f32_32x32x16_bf16 v[80:95], v[204:207], v[208:211], v[80:95]
	v_add3_u32 v204, v193, v196, s10
	ds_read_b64 v[204:205], v204 offset:24576
	v_or_b32_e32 v206, v203, v196
	v_xad_u32 v206, v206, 16, s10
	ds_read_b64 v[206:207], v206 offset:16384
	ds_read_b64 v[208:209], v188
	ds_read_b64 v[210:211], v189
	s_waitcnt lgkmcnt(0)
	v_mfma_f32_32x32x16_bf16 v[80:95], v[204:207], v[208:211], v[80:95]
	v_add3_u32 v204, v193, v197, s10
	ds_read_b64 v[204:205], v204 offset:24576
	v_or_b32_e32 v206, v203, v197
	v_xad_u32 v206, v206, 16, s10
	ds_read_b64 v[206:207], v206 offset:16384
	ds_read_b64 v[208:209], v186
	ds_read_b64 v[210:211], v187
	s_waitcnt lgkmcnt(0)
	v_mfma_f32_32x32x16_bf16 v[80:95], v[204:207], v[208:211], v[80:95]
	v_add3_u32 v204, v193, v198, s10
	ds_read_b64 v[204:205], v204 offset:24576
	v_or_b32_e32 v206, v203, v198
	v_xad_u32 v206, v206, 16, s10
	ds_read_b64 v[206:207], v206 offset:16384
	ds_read_b64 v[208:209], v184
	ds_read_b64 v[210:211], v185
	s_waitcnt lgkmcnt(0)
	v_mfma_f32_32x32x16_bf16 v[80:95], v[204:207], v[208:211], v[80:95]
	v_add3_u32 v204, v193, v199, s10
	ds_read_b64 v[204:205], v204 offset:24576
	v_or_b32_e32 v206, v203, v199
	v_xad_u32 v206, v206, 16, s10
	ds_read_b64 v[206:207], v206 offset:16384
	ds_read_b64 v[208:209], v182
	ds_read_b64 v[210:211], v183
	s_waitcnt lgkmcnt(0)
	v_mfma_f32_32x32x16_bf16 v[80:95], v[204:207], v[208:211], v[80:95]
	v_add3_u32 v204, v193, v200, s10
	ds_read_b64 v[204:205], v204 offset:24576
	v_or_b32_e32 v206, v203, v200
	v_xad_u32 v206, v206, 16, s10
	ds_read_b64 v[206:207], v206 offset:16384
	ds_read_b64 v[208:209], v180
	ds_read_b64 v[210:211], v181
	s_waitcnt lgkmcnt(0)
	v_mfma_f32_32x32x16_bf16 v[80:95], v[204:207], v[208:211], v[80:95]
	v_add3_u32 v204, v193, v201, s10
	ds_read_b64 v[204:205], v204 offset:24576
	v_or_b32_e32 v206, v203, v201
	v_xad_u32 v206, v206, 16, s10
	ds_read_b64 v[206:207], v206 offset:16384
	ds_read_b64 v[208:209], v178
	ds_read_b64 v[210:211], v179
	s_waitcnt lgkmcnt(0)
	v_mfma_f32_32x32x16_bf16 v[80:95], v[204:207], v[208:211], v[80:95]
	ds_read_b128 v[204:207], v174 offset:128
	ds_read_b128 v[208:211], v174 offset:160
	s_waitcnt lgkmcnt(1)
	v_sub_f32_e32 v204, v204, v148
	v_cndmask_b32_e32 v204, v158, v204, vcc
	v_sub_f32_e32 v205, v205, v148
	v_cmp_lt_i32_e32 vcc, s6, v202
	v_exp_f32_e32 v204, v204
	s_movk_i32 s6, 0xffdd
	v_cndmask_b32_e32 v205, v158, v205, vcc
	v_exp_f32_e32 v205, v205
	v_cmp_lt_i32_e32 vcc, s6, v202
	s_movk_i32 s6, 0xffdc
	v_pk_mul_f32 v[80:81], v[80:81], v[204:205]
	v_sub_f32_e32 v204, v206, v148
	v_cndmask_b32_e32 v204, v158, v204, vcc
	v_sub_f32_e32 v205, v207, v148
	v_cmp_lt_i32_e32 vcc, s6, v202
	v_exp_f32_e32 v204, v204
	s_movk_i32 s6, 0xffd7
	v_cndmask_b32_e32 v205, v158, v205, vcc
	v_exp_f32_e32 v205, v205
	v_cmp_lt_i32_e32 vcc, s6, v202
	s_movk_i32 s6, 0xffd6
	v_add_f32_e32 v146, v146, v80
	v_pk_mul_f32 v[82:83], v[82:83], v[204:205]
	s_waitcnt lgkmcnt(0)
	v_sub_f32_e32 v204, v208, v148
	v_cndmask_b32_e32 v204, v158, v204, vcc
	v_sub_f32_e32 v205, v209, v148
	v_cmp_lt_i32_e32 vcc, s6, v202
	v_exp_f32_e32 v204, v204
	s_movk_i32 s6, 0xffd5
	v_cndmask_b32_e32 v205, v158, v205, vcc
	v_exp_f32_e32 v205, v205
	v_cmp_lt_i32_e32 vcc, s6, v202
	s_movk_i32 s6, 0xffd4
	v_add_f32_e32 v146, v81, v146
	v_pk_mul_f32 v[84:85], v[84:85], v[204:205]
	v_sub_f32_e32 v204, v210, v148
	v_cndmask_b32_e32 v204, v158, v204, vcc
	v_sub_f32_e32 v205, v211, v148
	v_cmp_lt_i32_e32 vcc, s6, v202
	v_exp_f32_e32 v204, v204
	s_movk_i32 s6, 0xffcf
	v_cndmask_b32_e32 v205, v158, v205, vcc
	v_exp_f32_e32 v205, v205
	v_cmp_lt_i32_e32 vcc, s6, v202
	s_movk_i32 s6, 0xffce
	v_add_f32_e32 v146, v82, v146
	v_pk_mul_f32 v[86:87], v[86:87], v[204:205]
	ds_read_b128 v[204:207], v174 offset:192
	v_add_f32_e32 v146, v83, v146
	v_cvt_pk_bf16_f32 v80, v80, v81
	v_cvt_pk_bf16_f32 v81, v82, v83
	v_cvt_pk_bf16_f32 v82, v84, v85
	s_waitcnt lgkmcnt(0)
	v_sub_f32_e32 v204, v204, v148
	v_cndmask_b32_e32 v204, v158, v204, vcc
	v_sub_f32_e32 v205, v205, v148
	v_cmp_lt_i32_e32 vcc, s6, v202
	v_exp_f32_e32 v204, v204
	s_movk_i32 s6, 0xffcd
	v_cndmask_b32_e32 v205, v158, v205, vcc
	v_exp_f32_e32 v205, v205
	v_cmp_lt_i32_e32 vcc, s6, v202
	s_movk_i32 s6, 0xffcc
	v_cvt_pk_bf16_f32 v83, v86, v87
	v_pk_mul_f32 v[88:89], v[88:89], v[204:205]
	v_sub_f32_e32 v204, v206, v148
	v_cndmask_b32_e32 v204, v158, v204, vcc
	v_sub_f32_e32 v205, v207, v148
	v_cmp_lt_i32_e32 vcc, s6, v202
	v_exp_f32_e32 v204, v204
	s_movk_i32 s6, 0xffc7
	v_cndmask_b32_e32 v205, v158, v205, vcc
	v_exp_f32_e32 v205, v205
	v_cmp_lt_i32_e32 vcc, s6, v202
	s_movk_i32 s6, 0xffc6
	v_mfma_f32_32x32x16_bf16 v[64:79], v[80:83], v[100:103], v[64:79]
	v_mul_f32_e64 v90, v90, v204
	v_mul_f32_e64 v91, v91, v205
	ds_read_b128 v[204:207], v174 offset:224
	v_cvt_pk_bf16_f32 v80, v88, v89
	v_cvt_pk_bf16_f32 v81, v90, v91
	v_add_f32_e32 v146, v84, v146
	v_add_f32_e32 v146, v85, v146
	s_waitcnt lgkmcnt(0)
	v_sub_f32_e32 v204, v204, v148
	v_cndmask_b32_e32 v204, v158, v204, vcc
	v_sub_f32_e32 v205, v205, v148
	v_cmp_lt_i32_e32 vcc, s6, v202
	v_exp_f32_e32 v204, v204
	s_movk_i32 s6, 0xffc5
	v_cndmask_b32_e32 v205, v158, v205, vcc
	v_exp_f32_e32 v205, v205
	v_cmp_lt_i32_e32 vcc, s6, v202
	s_movk_i32 s6, 0xffc4
	v_add_f32_e32 v146, v86, v146
	v_pk_mul_f32 v[92:93], v[92:93], v[204:205]
	v_sub_f32_e32 v204, v206, v148
	v_cndmask_b32_e32 v204, v158, v204, vcc
	v_sub_f32_e32 v148, v207, v148
	v_cmp_lt_i32_e32 vcc, s6, v202
	v_exp_f32_e32 v204, v204
	v_cvt_pk_bf16_f32 v82, v92, v93
	v_cndmask_b32_e32 v148, v158, v148, vcc
	v_exp_f32_e32 v205, v148
	v_add_f32_e32 v146, v87, v146
	v_add_f32_e32 v146, v88, v146
	v_add_f32_e32 v146, v89, v146
	v_pk_mul_f32 v[94:95], v[94:95], v[204:205]
	v_add_f32_e32 v146, v90, v146
	v_cvt_pk_bf16_f32 v83, v94, v95
	v_add_f32_e32 v146, v91, v146
	v_add_f32_e32 v146, v92, v146
	v_mfma_f32_32x32x16_bf16 v[64:79], v[80:83], v[96:99], v[64:79]
	v_add_f32_e32 v146, v93, v146
	v_add_f32_e32 v146, v94, v146
	v_add_f32_e32 v146, v95, v146

; #define LAS __attribute__((address_space(3)))
; #define MFMA32(a, b, c) __builtin_amdgcn_mfma_f32_32x32x16_bf16((a), (b), (c), 0, 0, 0)
; DI bf16x8 pack_step(const f32x16& x, int s) { u32x4 p = {pk2(x[8 * s], x[8 * s + 1]), pk2(x[8 * s + 2], x[8 * s + 3]), pk2(x[8 * s + 4], x[8 * s + 5]), pk2(x[8 * s + 6], x[8 * s + 7])}; return __builtin_bit_cast(bf16x8, p); }
; DI bf16x8 ldsfrag(const LAS unsigned char* buf, unsigned o) { const s16x4 lo = *(const LAS s16x4*)(buf + o), hi = *(const LAS s16x4*)(buf + (o ^ 16u)); return __builtin_shufflevector(lo, hi, 0, 1, 2, 3, 4, 5, 6, 7); }
; DI void scan_phase(const Args& A, LAS unsigned char* lds, int wv) {
;     ...
;                 for (int sb = 0; sb < 2; ++sb) {
;                     __builtin_amdgcn_sched_barrier(0);
;                     if (sb != tb && (dir ? sb < tb : sb > tb)) continue;
;                     const unsigned ko = qro + sb * 8192u;
;                     f32x16 st;
; #pragma unroll
;                     for (int i = 0; i < 16; ++i) st[i] = 0.f;
; #pragma unroll
;                     for (int kk = 0; kk < 8; ++kk) { const unsigned c = ((2u * kk) ^ xr) << 4; st = MFMA32(ldsfrag(Kb, ko + c), ldsfrag(Qb, qo + c), st); }
; #pragma unroll
;                     for (int g = 0; g < 4; ++g) { const f32x4 uv = *(const LAS f32x4*)(wh + 32 * sb + 8 * g);
; #pragma unroll
;                         for (int q = 0; q < 4; ++q) {
;                             const int sc = 32 * sb + q + 8 * g;
;                             const int sp = sbase + sgn * sc;
;                             st[4 * g + q] *= __builtin_amdgcn_exp2f((sp <= tp) ? uv[q] - pmt : -1e30f);
;                             ds += st[4 * g + q];
;                         } }
;                     ha = MFMA32(pack_step(st, 0), vf[2 * sb], ha);
;                     ha = MFMA32(pack_step(st, 1), vf[2 * sb + 1], ha);
;                 }
;                 ds += __shfl_xor(ds, 32);
;                 {
;                     const float den = wr[128 + 32 * tb] * qnv + ds;
;                     const float rd = 1.0f / fmaxf(fabsf(den), wr[192 + 32 * tb]);
;                     if (h4 == 0) wr[320 + 32 * tb] = rd;
;                 }
.LBB0_1236:
	ds_read_b64 v[128:129], v148 offset:8192
	ds_read_b64 v[130:131], v149
	ds_read_b64 v[136:137], v148 offset:24576
	ds_read_b64 v[138:139], v149 offset:16384
	ds_read_b64 v[252:253], v202 offset:8192
	ds_read_b64 v[254:255], v195
	ds_read_b64 v[248:249], v202 offset:24576
	ds_read_b64 v[250:251], v195 offset:16384
	v_cmp_le_i32_e32 vcc, s95, v125
	s_waitcnt lgkmcnt(4)
	v_mfma_f32_32x32x16_bf16 v[80:95], v[136:139], v[128:131], 0
	ds_read_b64 v[128:129], v194 offset:8192
	ds_read_b64 v[130:131], v192
	ds_read_b64 v[136:137], v194 offset:24576
	ds_read_b64 v[138:139], v192 offset:16384
	s_waitcnt lgkmcnt(4)
	v_mfma_f32_32x32x16_bf16 v[80:95], v[248:251], v[252:255], v[80:95]
	ds_read_b64 v[252:253], v147 offset:8192
	ds_read_b64 v[254:255], v123
	ds_read_b64 v[248:249], v147 offset:24576
	ds_read_b64 v[250:251], v123 offset:16384
	s_waitcnt lgkmcnt(4)
	v_mfma_f32_32x32x16_bf16 v[80:95], v[136:139], v[128:131], v[80:95]
	ds_read_b64 v[128:129], v122 offset:8192
	ds_read_b64 v[130:131], v121
	ds_read_b64 v[136:137], v122 offset:24576
	ds_read_b64 v[138:139], v121 offset:16384
	s_waitcnt lgkmcnt(4)
	v_mfma_f32_32x32x16_bf16 v[80:95], v[248:251], v[252:255], v[80:95]
	ds_read_b64 v[252:253], v120 offset:8192
	ds_read_b64 v[254:255], v119
	ds_read_b64 v[248:249], v120 offset:24576
	ds_read_b64 v[250:251], v119 offset:16384
	s_waitcnt lgkmcnt(4)
	v_mfma_f32_32x32x16_bf16 v[80:95], v[136:139], v[128:131], v[80:95]
	ds_read_b64 v[128:129], v118 offset:8192
	ds_read_b64 v[130:131], v117
	ds_read_b64 v[136:137], v118 offset:24576
	ds_read_b64 v[138:139], v117 offset:16384
	s_waitcnt lgkmcnt(4)
	v_mfma_f32_32x32x16_bf16 v[80:95], v[248:251], v[252:255], v[80:95]
	ds_read_b64 v[252:253], v114 offset:8192
	ds_read_b64 v[254:255], v112
	ds_read_b64 v[248:249], v114 offset:24576
	ds_read_b64 v[250:251], v112 offset:16384
	s_waitcnt lgkmcnt(4)
	v_mfma_f32_32x32x16_bf16 v[80:95], v[136:139], v[128:131], v[80:95]
	s_waitcnt lgkmcnt(0)
	v_mfma_f32_32x32x16_bf16 v[80:95], v[248:251], v[252:255], v[80:95]
	ds_read_b128 v[118:121], v174 offset:128
	ds_read_b128 v[128:131], v174 offset:160
	s_waitcnt lgkmcnt(1)
	v_sub_f32_e32 v112, v118, v124
	v_cndmask_b32_e32 v112, v158, v112, vcc
	v_exp_f32_e32 v118, v112
	v_sub_f32_e32 v112, v119, v124
	v_cmp_le_i32_e32 vcc, s96, v125
	v_sub_f32_e32 v114, v120, v124
	s_nop 0
	v_cndmask_b32_e32 v112, v158, v112, vcc
	v_exp_f32_e32 v119, v112
	v_cmp_le_i32_e32 vcc, s57, v125
	v_pk_mul_f32 v[80:81], v[80:81], v[118:119]
	s_nop 0
	v_cndmask_b32_e32 v114, v158, v114, vcc
	v_exp_f32_e32 v118, v114
	v_sub_f32_e32 v114, v121, v124
	v_cmp_le_i32_e32 vcc, s40, v125
	v_add_f32_e32 v112, v126, v80
	v_add_f32_e32 v112, v81, v112
	v_cndmask_b32_e32 v114, v158, v114, vcc
	v_exp_f32_e32 v119, v114
	s_waitcnt lgkmcnt(0)
	v_sub_f32_e32 v114, v128, v124
	v_cmp_le_i32_e32 vcc, s41, v125
	v_cvt_pk_bf16_f32 v80, v80, v81
	v_pk_mul_f32 v[82:83], v[82:83], v[118:119]
	v_cndmask_b32_e32 v114, v158, v114, vcc
	v_exp_f32_e32 v118, v114
	v_sub_f32_e32 v114, v129, v124
	v_cmp_le_i32_e32 vcc, s42, v125
	v_add_f32_e32 v112, v82, v112
	v_add_f32_e32 v112, v83, v112
	v_cndmask_b32_e32 v114, v158, v114, vcc
	v_exp_f32_e32 v119, v114
	v_sub_f32_e32 v114, v130, v124
	v_cmp_le_i32_e32 vcc, s43, v125
	v_cvt_pk_bf16_f32 v81, v82, v83
	v_pk_mul_f32 v[84:85], v[84:85], v[118:119]
	v_cndmask_b32_e32 v114, v158, v114, vcc
	v_exp_f32_e32 v118, v114
	v_sub_f32_e32 v114, v131, v124
	v_cmp_le_i32_e32 vcc, s48, v125
	v_cvt_pk_bf16_f32 v82, v84, v85
	v_add_f32_e32 v112, v84, v112
	v_cndmask_b32_e32 v114, v158, v114, vcc
	v_exp_f32_e32 v119, v114
	v_cmp_le_i32_e32 vcc, s49, v125
	v_add_f32_e32 v112, v85, v112
	v_pk_mul_f32 v[86:87], v[86:87], v[118:119]
	ds_read_b128 v[118:121], v174 offset:192
	v_cvt_pk_bf16_f32 v83, v86, v87
	v_add_f32_e32 v112, v86, v112
	v_add_f32_e32 v112, v87, v112
	v_mfma_f32_32x32x16_bf16 v[64:79], v[80:83], v[100:103], v[64:79]
	s_waitcnt lgkmcnt(0)
	v_sub_f32_e32 v114, v118, v124
	v_cndmask_b32_e32 v114, v158, v114, vcc
	v_exp_f32_e32 v118, v114
	v_sub_f32_e32 v114, v119, v124
	v_cmp_le_i32_e32 vcc, s50, v125
	s_nop 1
	v_cndmask_b32_e32 v114, v158, v114, vcc
	v_exp_f32_e32 v119, v114
	v_sub_f32_e32 v114, v120, v124
	v_cmp_le_i32_e32 vcc, s51, v125
	v_pk_mul_f32 v[88:89], v[88:89], v[118:119]
	s_nop 0
	v_cndmask_b32_e32 v114, v158, v114, vcc
	v_exp_f32_e32 v118, v114
	v_sub_f32_e32 v114, v121, v124
	v_cmp_le_i32_e32 vcc, s53, v125
	v_add_f32_e32 v112, v88, v112
	v_cvt_pk_bf16_f32 v80, v88, v89
	v_cndmask_b32_e32 v114, v158, v114, vcc
	v_exp_f32_e32 v119, v114
	v_cmp_le_i32_e32 vcc, s3, v125
	v_add_f32_e32 v112, v89, v112
	v_pk_mul_f32 v[90:91], v[90:91], v[118:119]
	ds_read_b128 v[118:121], v174 offset:224
	v_cvt_pk_bf16_f32 v81, v90, v91
	v_add_f32_e32 v112, v90, v112
	v_add_f32_e32 v112, v91, v112
	s_waitcnt lgkmcnt(0)
	v_sub_f32_e32 v114, v118, v124
	v_cndmask_b32_e32 v114, v158, v114, vcc
	v_exp_f32_e32 v118, v114
	v_sub_f32_e32 v114, v119, v124
	v_cmp_le_i32_e32 vcc, s2, v125
	s_nop 1
	v_cndmask_b32_e32 v114, v158, v114, vcc
	v_exp_f32_e32 v119, v114
	v_sub_f32_e32 v114, v120, v124
	v_cmp_le_i32_e32 vcc, s28, v125
	v_pk_mul_f32 v[92:93], v[92:93], v[118:119]
	s_nop 0
	v_cndmask_b32_e32 v114, v158, v114, vcc
	v_exp_f32_e32 v118, v114
	v_sub_f32_e32 v114, v121, v124
	v_cmp_le_i32_e32 vcc, s29, v125
	v_cvt_pk_bf16_f32 v82, v92, v93
	v_add_f32_e32 v112, v92, v112
	v_cndmask_b32_e32 v114, v158, v114, vcc
	v_exp_f32_e32 v119, v114
	v_add_f32_e32 v112, v93, v112
	v_pk_mul_f32 v[94:95], v[94:95], v[118:119]
	s_nop 0
	v_cvt_pk_bf16_f32 v83, v94, v95
	v_add_f32_e32 v112, v94, v112
	v_add_f32_e32 v112, v95, v112
	v_mfma_f32_32x32x16_bf16 v[64:79], v[80:83], v[96:99], v[64:79]
	ds_bpermute_b32 v114, v169, v112
	s_and_saveexec_b64 s[8:9], s[6:7]
	s_cbranch_execz .LBB0_1238
	ds_read2_b32 v[80:81], v168 offset0:160 offset1:224
	s_waitcnt lgkmcnt(1)
	v_pk_add_f32 v[82:83], v[112:113], v[114:115]
	s_waitcnt lgkmcnt(0)
	v_fmac_f32_e32 v82, v83, v80
	v_max_f32_e32 v80, v81, v81
	v_max_f32_e64 v80, |v82|, v80
	v_div_scale_f32 v81, s[12:13], v80, v80, 1.0
	v_rcp_f32_e32 v82, v81
	v_div_scale_f32 v83, vcc, 1.0, v80, 1.0
	v_fma_f32 v84, -v81, v82, 1.0
	v_fmac_f32_e32 v82, v84, v82
	v_mul_f32_e32 v84, v83, v82
	v_fma_f32 v85, -v81, v84, v83
	v_fmac_f32_e32 v84, v85, v82
	v_fma_f32 v81, -v81, v84, v83
	v_div_fmas_f32 v81, v81, v82, v84
	v_div_fixup_f32 v80, v81, v80, 1.0
	ds_write_b32 v168, v80 offset:1408
